# v39 + P3 sample-row GEMM operands staged through LDS with full-line LDS-DMA (8 rows x 128 B per instruction) instead of 64-byte fragment loads
# speedup vs baseline: 1.0201x; 1.0050x over previous
.LBB0_338:
	v_lshrrev_b32_e32 v71, 6, v236
	v_and_b32_e32 v168, 15, v236
	v_readfirstlane_b32 vcc_lo, v71
	v_bfe_u32 v169, v236, 4, 2
	s_nop 3
	s_mul_i32 s10, vcc_lo, 6
	s_mul_i32 s11, vcc_lo, 5
	s_add_i32 s11, s11, 4
	s_cmp_lt_u32 vcc_lo, 4
	s_cselect_b32 s10, s10, s11
	s_cselect_b32 s11, 6, 5
	s_lshl_b32 s10, s10, 7
	s_lshl_b32 s12, vcc_lo, 14
	s_lshr_b32 vcc_hi, s15, 4
	s_mul_i32 vcc_hi, vcc_hi, 0x58000
	s_add_u32 vcc_hi, vcc_hi, s10
	s_add_u32 s16, s74, 0xb000000
	s_addc_u32 s17, s75, 0
	s_add_u32 s16, s16, vcc_hi
	s_addc_u32 s17, s17, 0
	s_and_b32 vcc_hi, s15, 15
	s_mul_i32 vcc_hi, vcc_hi, 0x58000
	s_add_u32 vcc_hi, vcc_hi, s10
	s_add_u32 s18, s74, 0xc00000
	s_addc_u32 s19, s75, 0
	s_add_u32 s18, s18, vcc_hi
	s_addc_u32 s19, s19, 0
	v_and_b32_e32 v53, 7, v168
	v_xor_b32_e32 v53, v53, v169
	v_lshlrev_b32_e32 v53, 4, v53
	v_lshl_add_u32 v52, v168, 7, v53
	v_add_u32_e32 v52, s12, v52
	v_xor_b32_e32 v53, 64, v52
	v_and_b32_e32 v36, 63, v236
	v_lshrrev_b32_e32 v164, 3, v36
	v_and_b32_e32 v36, 7, v36
	v_xor_b32_e32 v36, v36, v164
	v_mul_u32_u24_e32 v164, 0x1600, v164
	v_lshl_add_u32 v36, v36, 4, v164
	v_lshlrev_b32_e32 v71, 14, v71
	v_lshl_or_b32 v71, v168, 8, v71
	v_or_b32_e32 v156, 0, v169
	v_xor_b32_e32 v156, v156, v168
	v_lshl_or_b32 v156, v156, 4, v71
	v_or_b32_e32 v157, 4, v169
	v_xor_b32_e32 v157, v157, v168
	v_lshl_or_b32 v157, v157, 4, v71
	v_or_b32_e32 v158, 8, v169
	v_xor_b32_e32 v158, v158, v168
	v_lshl_or_b32 v158, v158, 4, v71
	v_or_b32_e32 v159, 12, v169
	v_xor_b32_e32 v159, v159, v168
	v_lshl_or_b32 v159, v159, 4, v71
	v_lshrrev_b32_e32 v71, 3, v236
	v_and_b32_e32 v168, 7, v236
	v_lshlrev_b32_e32 v169, 1, v168
	v_bitop3_b32 v169, v169, v71, 15 bitop3:0x78
	v_lshlrev_b32_e32 v169, 4, v169
	v_lshl_or_b32 v160, v71, 8, v169
	v_xor_b32_e32 v161, 16, v160
	v_add_u32_e32 v162, 0x10000, v160
	v_add_u32_e32 v163, 0x10000, v161
	s_lshr_b32 vcc_lo, s15, 4
	s_lshl_b32 vcc_lo, vcc_lo, 6
	s_and_b32 vcc_hi, s15, 15
	s_lshl_b32 vcc_hi, vcc_hi, 6
	v_add_u32_e32 v71, vcc_lo, v71
	v_lshl_add_u32 v168, v168, 3, vcc_hi
	v_lshlrev_b32_e32 v168, 2, v168
	v_lshl_add_u32 v165, v71, 12, v168
	v_lshrrev_b32_e32 v71, 6, v71
	v_add_u32_e32 v71, 8, v71
	v_mul_u32_u24_e32 v71, 0x9000, v71
	v_add_u32_e32 v164, v71, v168
	v_mov_b32_e32 v0, 0
	v_mov_b32_e32 v1, 0
	v_mov_b32_e32 v2, 0
	v_mov_b32_e32 v3, 0
	v_mov_b32_e32 v4, 0
	v_mov_b32_e32 v5, 0
	v_mov_b32_e32 v6, 0
	v_mov_b32_e32 v7, 0
	v_mov_b32_e32 v8, 0
	v_mov_b32_e32 v9, 0
	v_mov_b32_e32 v10, 0
	v_mov_b32_e32 v11, 0
	v_mov_b32_e32 v12, 0
	v_mov_b32_e32 v13, 0
	v_mov_b32_e32 v14, 0
	v_mov_b32_e32 v15, 0
	v_mov_b32_e32 v16, 0
	v_mov_b32_e32 v17, 0
	v_mov_b32_e32 v18, 0
	v_mov_b32_e32 v19, 0
	v_mov_b32_e32 v20, 0
	v_mov_b32_e32 v21, 0
	v_mov_b32_e32 v22, 0
	v_mov_b32_e32 v23, 0
	v_mov_b32_e32 v24, 0
	v_mov_b32_e32 v25, 0
	v_mov_b32_e32 v26, 0
	v_mov_b32_e32 v27, 0
	v_mov_b32_e32 v28, 0
	v_mov_b32_e32 v29, 0
	v_mov_b32_e32 v30, 0
	v_mov_b32_e32 v31, 0
	v_mov_b32_e32 v32, 0
	v_mov_b32_e32 v33, 0
	v_mov_b32_e32 v34, 0
	v_mov_b32_e32 v35, 0
	v_mov_b32_e32 v44, 0
	v_mov_b32_e32 v45, 0
	v_mov_b32_e32 v46, 0
	v_mov_b32_e32 v47, 0
	v_mov_b32_e32 v48, 0
	v_mov_b32_e32 v49, 0
	v_mov_b32_e32 v50, 0
	v_mov_b32_e32 v51, 0
	v_mov_b32_e32 v72, 0
	v_mov_b32_e32 v73, 0
	v_mov_b32_e32 v74, 0
	v_mov_b32_e32 v75, 0
	v_mov_b32_e32 v76, 0
	v_mov_b32_e32 v77, 0
	v_mov_b32_e32 v78, 0
	v_mov_b32_e32 v79, 0
	v_mov_b32_e32 v80, 0
	v_mov_b32_e32 v81, 0
	v_mov_b32_e32 v82, 0
	v_mov_b32_e32 v83, 0
	v_mov_b32_e32 v84, 0
	v_mov_b32_e32 v85, 0
	v_mov_b32_e32 v86, 0
	v_mov_b32_e32 v87, 0
	v_mov_b32_e32 v88, 0
	v_mov_b32_e32 v89, 0
	v_mov_b32_e32 v90, 0
	v_mov_b32_e32 v91, 0
	s_mov_b32 s10, 0
.Lsg2p3_loop:
	s_mov_b64 s[40:41], s[16:17]
	s_mov_b32 m0, s12
	s_nop 0
	global_load_lds_dwordx4 v36, s[40:41]
	s_add_u32 s40, s40, 0xb000
	s_addc_u32 s41, s41, 0
	s_add_i32 m0, s12, 0x400
	s_nop 0
	global_load_lds_dwordx4 v36, s[40:41]
	s_add_u32 s40, s40, 0xb000
	s_addc_u32 s41, s41, 0
	s_add_i32 m0, s12, 0x800
	s_nop 0
	global_load_lds_dwordx4 v36, s[40:41]
	s_add_u32 s40, s40, 0xb000
	s_addc_u32 s41, s41, 0
	s_add_i32 m0, s12, 0xc00
	s_nop 0
	global_load_lds_dwordx4 v36, s[40:41]
	s_add_u32 s40, s40, 0xb000
	s_addc_u32 s41, s41, 0
	s_add_i32 m0, s12, 0x1000
	s_nop 0
	global_load_lds_dwordx4 v36, s[40:41]
	s_add_u32 s40, s40, 0xb000
	s_addc_u32 s41, s41, 0
	s_add_i32 m0, s12, 0x1400
	s_nop 0
	global_load_lds_dwordx4 v36, s[40:41]
	s_add_u32 s40, s40, 0xb000
	s_addc_u32 s41, s41, 0
	s_add_i32 m0, s12, 0x1800
	s_nop 0
	global_load_lds_dwordx4 v36, s[40:41]
	s_add_u32 s40, s40, 0xb000
	s_addc_u32 s41, s41, 0
	s_add_i32 m0, s12, 0x1c00
	s_nop 0
	global_load_lds_dwordx4 v36, s[40:41]
	s_mov_b64 s[44:45], s[18:19]
	s_add_i32 m0, s12, 0x2000
	s_nop 0
	global_load_lds_dwordx4 v36, s[44:45]
	s_add_u32 s44, s44, 0xb000
	s_addc_u32 s45, s45, 0
	s_add_i32 m0, s12, 0x2400
	s_nop 0
	global_load_lds_dwordx4 v36, s[44:45]
	s_add_u32 s44, s44, 0xb000
	s_addc_u32 s45, s45, 0
	s_add_i32 m0, s12, 0x2800
	s_nop 0
	global_load_lds_dwordx4 v36, s[44:45]
	s_add_u32 s44, s44, 0xb000
	s_addc_u32 s45, s45, 0
	s_add_i32 m0, s12, 0x2c00
	s_nop 0
	global_load_lds_dwordx4 v36, s[44:45]
	s_add_u32 s44, s44, 0xb000
	s_addc_u32 s45, s45, 0
	s_add_i32 m0, s12, 0x3000
	s_nop 0
	global_load_lds_dwordx4 v36, s[44:45]
	s_add_u32 s44, s44, 0xb000
	s_addc_u32 s45, s45, 0
	s_add_i32 m0, s12, 0x3400
	s_nop 0
	global_load_lds_dwordx4 v36, s[44:45]
	s_add_u32 s44, s44, 0xb000
	s_addc_u32 s45, s45, 0
	s_add_i32 m0, s12, 0x3800
	s_nop 0
	global_load_lds_dwordx4 v36, s[44:45]
	s_add_u32 s44, s44, 0xb000
	s_addc_u32 s45, s45, 0
	s_add_i32 m0, s12, 0x3c00
	s_nop 0
	global_load_lds_dwordx4 v36, s[44:45]
	s_add_u32 s16, s16, 0x80
	s_addc_u32 s17, s17, 0
	s_add_u32 s18, s18, 0x80
	s_addc_u32 s19, s19, 0
	s_waitcnt vmcnt(0)
	ds_read_b128 v[92:95], v52
	ds_read_b128 v[96:99], v52 offset:2048
	ds_read_b128 v[100:103], v52 offset:4096
	ds_read_b128 v[104:107], v52 offset:6144
	ds_read_b128 v[124:127], v52 offset:8192
	ds_read_b128 v[128:131], v52 offset:10240
	ds_read_b128 v[132:135], v52 offset:12288
	ds_read_b128 v[136:139], v52 offset:14336
	ds_read_b128 v[108:111], v53
	ds_read_b128 v[112:115], v53 offset:2048
	ds_read_b128 v[116:119], v53 offset:4096
	ds_read_b128 v[120:123], v53 offset:6144
	ds_read_b128 v[140:143], v53 offset:8192
	ds_read_b128 v[144:147], v53 offset:10240
	ds_read_b128 v[148:151], v53 offset:12288
	ds_read_b128 v[152:155], v53 offset:14336
	s_waitcnt lgkmcnt(8)
	v_mfma_f32_16x16x32_bf16 v[0:3], v[124:127], v[92:95], v[0:3]
	v_mfma_f32_16x16x32_bf16 v[4:7], v[128:131], v[92:95], v[4:7]
	v_mfma_f32_16x16x32_bf16 v[8:11], v[132:135], v[92:95], v[8:11]
	v_mfma_f32_16x16x32_bf16 v[12:15], v[136:139], v[92:95], v[12:15]
	v_mfma_f32_16x16x32_bf16 v[16:19], v[124:127], v[96:99], v[16:19]
	v_mfma_f32_16x16x32_bf16 v[20:23], v[128:131], v[96:99], v[20:23]
	v_mfma_f32_16x16x32_bf16 v[24:27], v[132:135], v[96:99], v[24:27]
	v_mfma_f32_16x16x32_bf16 v[28:31], v[136:139], v[96:99], v[28:31]
	v_mfma_f32_16x16x32_bf16 v[32:35], v[124:127], v[100:103], v[32:35]
	v_mfma_f32_16x16x32_bf16 v[44:47], v[128:131], v[100:103], v[44:47]
	v_mfma_f32_16x16x32_bf16 v[48:51], v[132:135], v[100:103], v[48:51]
	v_mfma_f32_16x16x32_bf16 v[72:75], v[136:139], v[100:103], v[72:75]
	v_mfma_f32_16x16x32_bf16 v[76:79], v[124:127], v[104:107], v[76:79]
	v_mfma_f32_16x16x32_bf16 v[80:83], v[128:131], v[104:107], v[80:83]
	v_mfma_f32_16x16x32_bf16 v[84:87], v[132:135], v[104:107], v[84:87]
	v_mfma_f32_16x16x32_bf16 v[88:91], v[136:139], v[104:107], v[88:91]
	s_waitcnt lgkmcnt(0)
	v_mfma_f32_16x16x32_bf16 v[0:3], v[140:143], v[108:111], v[0:3]
	v_mfma_f32_16x16x32_bf16 v[4:7], v[144:147], v[108:111], v[4:7]
	v_mfma_f32_16x16x32_bf16 v[8:11], v[148:151], v[108:111], v[8:11]
	v_mfma_f32_16x16x32_bf16 v[12:15], v[152:155], v[108:111], v[12:15]
	v_mfma_f32_16x16x32_bf16 v[16:19], v[140:143], v[112:115], v[16:19]
	v_mfma_f32_16x16x32_bf16 v[20:23], v[144:147], v[112:115], v[20:23]
	v_mfma_f32_16x16x32_bf16 v[24:27], v[148:151], v[112:115], v[24:27]
	v_mfma_f32_16x16x32_bf16 v[28:31], v[152:155], v[112:115], v[28:31]
	v_mfma_f32_16x16x32_bf16 v[32:35], v[140:143], v[116:119], v[32:35]
	v_mfma_f32_16x16x32_bf16 v[44:47], v[144:147], v[116:119], v[44:47]
	v_mfma_f32_16x16x32_bf16 v[48:51], v[148:151], v[116:119], v[48:51]
	v_mfma_f32_16x16x32_bf16 v[72:75], v[152:155], v[116:119], v[72:75]
	v_mfma_f32_16x16x32_bf16 v[76:79], v[140:143], v[120:123], v[76:79]
	v_mfma_f32_16x16x32_bf16 v[80:83], v[144:147], v[120:123], v[80:83]
	v_mfma_f32_16x16x32_bf16 v[84:87], v[148:151], v[120:123], v[84:87]
	v_mfma_f32_16x16x32_bf16 v[88:91], v[152:155], v[120:123], v[88:91]
	s_add_i32 s10, s10, 1
	s_cmp_lt_u32 s10, s11
	s_cbranch_scc1 .Lsg2p3_loop
	s_add_u32 s16, s74, 0x2000
	s_addc_u32 s17, s75, 0
	s_mov_b32 s18, s38
	s_mov_b32 s19, s39
	s_nop 7
	s_nop 7
	global_load_dwordx4 v[92:95], v164, s[16:17]
	global_load_dwordx4 v[96:99], v164, s[16:17] offset:16
	global_load_dwordx4 v[100:103], v165, s[18:19]
	global_load_dwordx4 v[104:107], v165, s[18:19] offset:16
	ds_write_b128 v156, v[0:3]
	ds_write_b128 v157, v[4:7]
	ds_write_b128 v158, v[8:11]
	ds_write_b128 v159, v[12:15]
	ds_write_b128 v156, v[16:19] offset:4096
	ds_write_b128 v157, v[20:23] offset:4096
	ds_write_b128 v158, v[24:27] offset:4096
	ds_write_b128 v159, v[28:31] offset:4096
	ds_write_b128 v156, v[32:35] offset:8192
	ds_write_b128 v157, v[44:47] offset:8192
	ds_write_b128 v158, v[48:51] offset:8192
	ds_write_b128 v159, v[72:75] offset:8192
	ds_write_b128 v156, v[76:79] offset:12288
	ds_write_b128 v157, v[80:83] offset:12288
	ds_write_b128 v158, v[84:87] offset:12288
	ds_write_b128 v159, v[88:91] offset:12288
	s_add_u32 s18, s72, 0x4000000
	s_addc_u32 s19, s73, 0
	s_waitcnt lgkmcnt(0)
	s_barrier
	ds_read_b128 v[0:3], v160
	ds_read_b128 v[32:35], v161
	ds_read_b128 v[4:7], v160 offset:16384
	ds_read_b128 v[44:47], v161 offset:16384
	ds_read_b128 v[8:11], v160 offset:32768
	ds_read_b128 v[48:51], v161 offset:32768
	ds_read_b128 v[12:15], v160 offset:49152
	ds_read_b128 v[72:75], v161 offset:49152
	ds_read_b128 v[16:19], v162
	ds_read_b128 v[76:79], v163
	ds_read_b128 v[20:23], v162 offset:16384
	ds_read_b128 v[80:83], v163 offset:16384
	ds_read_b128 v[24:27], v162 offset:32768
	ds_read_b128 v[84:87], v163 offset:32768
	ds_read_b128 v[28:31], v162 offset:49152
	ds_read_b128 v[88:91], v163 offset:49152
	s_waitcnt vmcnt(0)
	v_pk_mul_f32 v[92:93], v[92:93], 0.5 op_sel_hi:[1,0]
	v_pk_mul_f32 v[94:95], v[94:95], 0.5 op_sel_hi:[1,0]
	v_pk_mul_f32 v[96:97], v[96:97], 0.5 op_sel_hi:[1,0]
	v_pk_mul_f32 v[98:99], v[98:99], 0.5 op_sel_hi:[1,0]
	s_waitcnt lgkmcnt(14)
	v_pk_add_f32 v[0:1], v[0:1], 0 op_sel_hi:[1,0]
	v_pk_add_f32 v[2:3], v[2:3], 0 op_sel_hi:[1,0]
	v_pk_add_f32 v[32:33], v[32:33], 0 op_sel_hi:[1,0]
	v_pk_add_f32 v[34:35], v[34:35], 0 op_sel_hi:[1,0]
	s_waitcnt lgkmcnt(12)
	v_pk_add_f32 v[0:1], v[0:1], v[4:5]
	v_pk_add_f32 v[2:3], v[2:3], v[6:7]
	v_pk_add_f32 v[32:33], v[32:33], v[44:45]
	v_pk_add_f32 v[34:35], v[34:35], v[46:47]
	s_waitcnt lgkmcnt(10)
	v_pk_add_f32 v[0:1], v[0:1], v[8:9]
	v_pk_add_f32 v[2:3], v[2:3], v[10:11]
	v_pk_add_f32 v[32:33], v[32:33], v[48:49]
	v_pk_add_f32 v[34:35], v[34:35], v[50:51]
	s_waitcnt lgkmcnt(8)
	v_pk_add_f32 v[0:1], v[0:1], v[12:13]
	v_pk_add_f32 v[2:3], v[2:3], v[14:15]
	v_pk_add_f32 v[32:33], v[32:33], v[72:73]
	v_pk_add_f32 v[34:35], v[34:35], v[74:75]
	s_waitcnt lgkmcnt(6)
	v_pk_add_f32 v[0:1], v[0:1], v[16:17]
	v_pk_add_f32 v[2:3], v[2:3], v[18:19]
	v_pk_add_f32 v[32:33], v[32:33], v[76:77]
	v_pk_add_f32 v[34:35], v[34:35], v[78:79]
	s_waitcnt lgkmcnt(4)
	v_pk_add_f32 v[0:1], v[0:1], v[20:21]
	v_pk_add_f32 v[2:3], v[2:3], v[22:23]
	v_pk_add_f32 v[32:33], v[32:33], v[80:81]
	v_pk_add_f32 v[34:35], v[34:35], v[82:83]
	s_waitcnt lgkmcnt(2)
	v_pk_add_f32 v[0:1], v[0:1], v[24:25]
	v_pk_add_f32 v[2:3], v[2:3], v[26:27]
	v_pk_add_f32 v[32:33], v[32:33], v[84:85]
	v_pk_add_f32 v[34:35], v[34:35], v[86:87]
	s_waitcnt lgkmcnt(0)
	v_pk_add_f32 v[0:1], v[0:1], v[28:29]
	v_pk_add_f32 v[2:3], v[2:3], v[30:31]
	v_pk_add_f32 v[32:33], v[32:33], v[88:89]
	v_pk_add_f32 v[34:35], v[34:35], v[90:91]
	v_pk_fma_f32 v[0:1], v[92:93], v[0:1], v[100:101]
	v_pk_fma_f32 v[2:3], v[94:95], v[2:3], v[102:103]
	v_pk_fma_f32 v[32:33], v[96:97], v[32:33], v[104:105]
	v_pk_fma_f32 v[34:35], v[98:99], v[34:35], v[106:107]
	global_store_dwordx4 v165, v[0:3], s[18:19]
	global_store_dwordx4 v165, v[32:35], s[18:19] offset:16
	s_barrier
	s_add_i32 s15, s15, s78
	s_add_i32 s2, s2, s3
	s_add_i32 s6, s6, s7
	s_cmpk_lt_i32 s15, 0x100
	s_cbranch_scc1 .LBB0_338
